# S5-B: C-matrix fragment loads (4 re/im pairs per state group) issued together with counted waits
# baseline (speedup 1.0000x reference)
.LBB0_495:
	s_or_b64 exec, exec, s[12:13]
	s_add_i32 s14, s51, s7
	s_ashr_i32 s15, s14, 31
	s_lshl_b64 s[14:15], s[14:15], 12
	v_lshl_or_b32 v36, v52, 2, s14
	v_mov_b32_e32 v37, s15
	s_waitcnt lgkmcnt(0)
	v_lshl_add_u64 v[50:51], s[38:39], 0, v[36:37]
	v_lshl_add_u64 v[48:49], s[36:37], 0, v[36:37]
	global_load_dwordx4 v[36:39], v[50:51], off
	global_load_dwordx4 v[32:35], v[48:49], off
	global_load_dwordx4 v[200:203], v[48:49], off offset:64
	global_load_dwordx4 v[204:207], v[50:51], off offset:64
	global_load_dwordx4 v[208:211], v[48:49], off offset:128
	global_load_dwordx4 v[212:215], v[50:51], off offset:128
	global_load_dwordx4 v[216:219], v[48:49], off offset:192
	global_load_dwordx4 v[220:223], v[50:51], off offset:192
	s_add_i32 s14, s51, s53
	s_ashr_i32 s15, s14, 31
	s_lshl_b64 s[14:15], s[14:15], 9
	s_xor_b64 s[12:13], s[56:57], -1
	v_add_u32_e32 v65, s1, v97
	v_add_u32_e32 v118, s1, v98
	v_pk_mov_b32 v[70:71], v[66:67], v[66:67] op_sel:[1,0]
	s_waitcnt vmcnt(7)
	v_xor_b32_e32 v36, 0x80000000, v36
	s_waitcnt vmcnt(6)
	v_cvt_pk_bf16_f32 v32, v32, v36
	v_xor_b32_e32 v36, 0x80000000, v37
	v_cvt_pk_bf16_f32 v33, v33, v36
	v_xor_b32_e32 v36, 0x80000000, v38
	v_cvt_pk_bf16_f32 v34, v34, v36
	v_xor_b32_e32 v36, 0x80000000, v39
	v_cvt_pk_bf16_f32 v35, v35, v36
	s_nop 0
	s_nop 0
	s_waitcnt vmcnt(4)
	v_xor_b32_e32 v40, 0x80000000, v204
	v_cvt_pk_bf16_f32 v36, v200, v40
	v_xor_b32_e32 v40, 0x80000000, v205
	v_cvt_pk_bf16_f32 v37, v201, v40
	v_xor_b32_e32 v40, 0x80000000, v206
	v_cvt_pk_bf16_f32 v38, v202, v40
	v_xor_b32_e32 v40, 0x80000000, v207
	v_cvt_pk_bf16_f32 v39, v203, v40
	s_nop 0
	s_nop 0
	s_waitcnt vmcnt(2)
	v_xor_b32_e32 v44, 0x80000000, v212
	v_cvt_pk_bf16_f32 v40, v208, v44
	v_xor_b32_e32 v44, 0x80000000, v213
	v_cvt_pk_bf16_f32 v41, v209, v44
	v_xor_b32_e32 v44, 0x80000000, v214
	v_cvt_pk_bf16_f32 v42, v210, v44
	v_xor_b32_e32 v44, 0x80000000, v215
	v_cvt_pk_bf16_f32 v43, v211, v44
	s_nop 0
	s_nop 0
	s_nop 0
	s_waitcnt vmcnt(0)
	v_xor_b32_e32 v48, 0x80000000, v220
	v_cvt_pk_bf16_f32 v44, v216, v48
	v_xor_b32_e32 v48, 0x80000000, v221
	v_cvt_pk_bf16_f32 v45, v217, v48
	v_xor_b32_e32 v48, 0x80000000, v222
	v_cvt_pk_bf16_f32 v46, v218, v48
	v_xor_b32_e32 v48, 0x80000000, v223
	v_cvt_pk_bf16_f32 v47, v219, v48
	v_lshl_add_u32 v48, s51, 4, v96
	v_ashrrev_i32_e32 v49, 31, v48
	v_lshl_add_u64 v[48:49], v[48:49], 2, s[28:29]
	global_load_dword v63, v[48:49], off
	v_lshl_add_u64 v[48:49], v[54:55], 0, s[14:15]
	global_load_dwordx2 v[68:69], v[48:49], off
